# NA attention softmax: one branch per tile on the local/context flag instead of computing both score transforms and selecting per element (v_sub + v_fma + v_cndmask -> one op)
# speedup vs baseline: 1.0082x; 1.0024x over previous
.LBB0_336:
	s_cmp_eq_u64 s[10:11], 0
	s_cbranch_scc1 .Lna_sm_local
	v_fma_f32 v66, v66, s17, -v144
	v_fma_f32 v67, v67, s17, -v144
	v_exp_f32_e32 v66, v66
	v_fma_f32 v68, v68, s17, -v144
	v_exp_f32_e32 v67, v67
	v_fma_f32 v69, v69, s17, -v144
	v_exp_f32_e32 v68, v68
	v_exp_f32_e32 v69, v69
	v_add_f32_e32 v82, 0, v66
	v_add_f32_e32 v82, v67, v82
	v_add_f32_e32 v82, v68, v82
	v_add_f32_e32 v82, v69, v82
	v_cvt_pk_bf16_f32 v66, v66, v67
	v_cvt_pk_bf16_f32 v67, v68, v69
	v_fma_f32 v68, v70, s17, -v144
	v_fma_f32 v70, v71, s17, -v144
	v_exp_f32_e32 v68, v68
	v_fma_f32 v71, v72, s17, -v144
	v_exp_f32_e32 v70, v70
	v_fma_f32 v72, v73, s17, -v144
	v_exp_f32_e32 v71, v71
	v_exp_f32_e32 v72, v72
	v_add_f32_e32 v69, v68, v82
	v_add_f32_e32 v69, v70, v69
	v_add_f32_e32 v69, v71, v69
	v_add_f32_e32 v73, v72, v69
	v_cvt_pk_bf16_f32 v68, v68, v70
	v_cvt_pk_bf16_f32 v69, v71, v72
	v_fma_f32 v70, v74, s17, -v144
	v_exp_f32_e32 v70, v70
	v_fma_f32 v74, v76, s17, -v144
	v_fma_f32 v83, v108, s17, -v142
	v_add_f32_e32 v71, v70, v73
	v_fma_f32 v72, v75, s17, -v144
	v_exp_f32_e32 v72, v72
	v_mov_b32_e32 v73, v74
	v_fma_f32 v74, v77, s17, -v144
	v_exp_f32_e32 v73, v73
	v_exp_f32_e32 v74, v74
	v_add_f32_e32 v71, v72, v71
	v_add_f32_e32 v71, v73, v71
	v_cvt_pk_bf16_f32 v70, v70, v72
	v_add_f32_e32 v75, v74, v71
	v_cvt_pk_bf16_f32 v71, v73, v74
	v_fma_f32 v72, v78, s17, -v144
	v_exp_f32_e32 v72, v72
	v_fma_f32 v76, v80, s17, -v144
	v_fma_f32 v77, v81, s17, -v144
	v_add_f32_e32 v73, v72, v75
	v_fma_f32 v74, v79, s17, -v144
	v_exp_f32_e32 v74, v74
	v_mov_b32_e32 v75, v76
	v_exp_f32_e32 v75, v75
	v_mov_b32_e32 v76, v77
	v_exp_f32_e32 v76, v76
	v_add_f32_e32 v73, v74, v73
	v_add_f32_e32 v73, v75, v73
	v_cvt_pk_bf16_f32 v72, v72, v74
	v_add_f32_e32 v77, v76, v73
	v_cvt_pk_bf16_f32 v73, v75, v76
	v_fma_f32 v74, v98, s17, -v142
	v_add_f32_e32 v140, v140, v77
	v_fma_f32 v76, v99, s17, -v142
	v_exp_f32_e32 v74, v74
	v_fma_f32 v77, v100, s17, -v142
	v_exp_f32_e32 v76, v76
	v_fma_f32 v78, v101, s17, -v142
	v_exp_f32_e32 v77, v77
	v_exp_f32_e32 v78, v78
	v_add_f32_e32 v75, 0, v74
	v_add_f32_e32 v75, v76, v75
	v_add_f32_e32 v75, v77, v75
	v_add_f32_e32 v79, v78, v75
	v_cvt_pk_bf16_f32 v74, v74, v76
	v_cvt_pk_bf16_f32 v75, v77, v78
	v_fma_f32 v76, v102, s17, -v142
	v_exp_f32_e32 v76, v76
	v_fma_f32 v80, v104, s17, -v142
	v_fma_f32 v81, v105, s17, -v142
	v_add_f32_e32 v77, v76, v79
	v_fma_f32 v78, v103, s17, -v142
	v_exp_f32_e32 v78, v78
	v_mov_b32_e32 v79, v80
	v_exp_f32_e32 v79, v79
	v_mov_b32_e32 v80, v81
	v_exp_f32_e32 v80, v80
	v_add_f32_e32 v77, v78, v77
	v_add_f32_e32 v77, v79, v77
	v_cvt_pk_bf16_f32 v76, v76, v78
	v_add_f32_e32 v81, v80, v77
	v_cvt_pk_bf16_f32 v77, v79, v80
	v_fma_f32 v78, v106, s17, -v142
	v_exp_f32_e32 v78, v78
	v_fma_f32 v84, v109, s17, -v142
	v_fma_f32 v85, v112, s17, -v142
	v_add_f32_e32 v79, v78, v81
	v_fma_f32 v80, v107, s17, -v142
	v_exp_f32_e32 v80, v80
	v_mov_b32_e32 v81, v83
	v_exp_f32_e32 v81, v81
	v_mov_b32_e32 v83, v84
	v_exp_f32_e32 v83, v83
	v_add_f32_e32 v79, v80, v79
	v_add_f32_e32 v79, v81, v79
	v_cvt_pk_bf16_f32 v78, v78, v80
	v_add_f32_e32 v84, v83, v79
	v_cvt_pk_bf16_f32 v79, v81, v83
	v_fma_f32 v80, v110, s17, -v142
	v_exp_f32_e32 v80, v80
	v_fma_f32 v86, v113, s17, -v142
	v_or_b32_e32 v82, s15, v135
	v_add_f32_e32 v81, v80, v84
	v_fma_f32 v83, v111, s17, -v142
	v_exp_f32_e32 v83, v83
	v_mov_b32_e32 v84, v85
	v_exp_f32_e32 v84, v84
	v_mov_b32_e32 v85, v86
	v_exp_f32_e32 v85, v85
	v_add_f32_e32 v81, v83, v81
	v_add_f32_e32 v81, v84, v81
	v_mul_u32_u24_e32 v82, 0x48, v82
	v_add_f32_e32 v86, v85, v81
	v_lshl_add_u32 v98, v82, 1, v136
	v_cvt_pk_bf16_f32 v80, v80, v83
	v_cvt_pk_bf16_f32 v81, v84, v85
	v_add_f32_e32 v137, v137, v86
	ds_read_b64_tr_b16 v[84:85], v98 offset:20736
	ds_read_b64_tr_b16 v[82:83], v98 offset:18432
	ds_read_b64_tr_b16 v[86:87], v98 offset:18464
	ds_read_b64_tr_b16 v[90:91], v98 offset:23040
	ds_read_b64_tr_b16 v[92:93], v98 offset:25344
	ds_read_b64_tr_b16 v[88:89], v98 offset:20768
	ds_read_b64_tr_b16 v[94:95], v98 offset:23072
	ds_read_b64_tr_b16 v[96:97], v98 offset:25376
	s_waitcnt lgkmcnt(6)
	v_mfma_f32_16x16x32_bf16 v[18:21], v[82:85], v[66:69], v[18:21]
	v_mfma_f32_16x16x32_bf16 v[30:33], v[82:85], v[74:77], v[30:33]
	s_waitcnt lgkmcnt(2)
	v_mfma_f32_16x16x32_bf16 v[22:25], v[86:89], v[66:69], v[22:25]
	v_mfma_f32_16x16x32_bf16 v[26:29], v[86:89], v[74:77], v[26:29]
	v_mfma_f32_16x16x32_bf16 v[18:21], v[90:93], v[70:73], v[18:21]
	v_mfma_f32_16x16x32_bf16 v[30:33], v[90:93], v[78:81], v[30:33]
	s_waitcnt lgkmcnt(0)
	v_mfma_f32_16x16x32_bf16 v[22:25], v[94:97], v[70:73], v[22:25]
	v_mfma_f32_16x16x32_bf16 v[26:29], v[94:97], v[78:81], v[26:29]
	ds_read_b64_tr_b16 v[84:85], v98 offset:20800
	ds_read_b64_tr_b16 v[82:83], v98 offset:18496
	ds_read_b64_tr_b16 v[88:89], v98 offset:20832
	ds_read_b64_tr_b16 v[86:87], v98 offset:18528
	ds_read_b64_tr_b16 v[90:91], v98 offset:23104
	ds_read_b64_tr_b16 v[92:93], v98 offset:25408
	ds_read_b64_tr_b16 v[96:97], v98 offset:25440
	ds_read_b64_tr_b16 v[94:95], v98 offset:23136
	s_waitcnt lgkmcnt(6)
	v_mfma_f32_16x16x32_bf16 v[10:13], v[82:85], v[66:69], v[10:13]
	v_mfma_f32_16x16x32_bf16 v[14:17], v[82:85], v[74:77], v[14:17]
	s_waitcnt lgkmcnt(4)
	v_mfma_f32_16x16x32_bf16 v[2:5], v[86:89], v[66:69], v[2:5]
	v_mfma_f32_16x16x32_bf16 v[6:9], v[86:89], v[74:77], v[6:9]
	s_waitcnt lgkmcnt(2)
	v_mfma_f32_16x16x32_bf16 v[10:13], v[90:93], v[70:73], v[10:13]
	v_mfma_f32_16x16x32_bf16 v[14:17], v[90:93], v[78:81], v[14:17]
	s_waitcnt lgkmcnt(0)
	v_mfma_f32_16x16x32_bf16 v[2:5], v[94:97], v[70:73], v[2:5]
	v_mfma_f32_16x16x32_bf16 v[6:9], v[94:97], v[78:81], v[6:9]
	s_branch .LBB0_337
.Lna_sm_local:
	v_sub_f32_e32 v66, v66, v144
	v_sub_f32_e32 v67, v67, v144
	v_exp_f32_e32 v66, v66
	v_sub_f32_e32 v68, v68, v144
	v_exp_f32_e32 v67, v67
	v_sub_f32_e32 v69, v69, v144
	v_exp_f32_e32 v68, v68
	v_exp_f32_e32 v69, v69
	v_add_f32_e32 v82, 0, v66
	v_add_f32_e32 v82, v67, v82
	v_add_f32_e32 v82, v68, v82
	v_add_f32_e32 v82, v69, v82
	v_cvt_pk_bf16_f32 v66, v66, v67
	v_cvt_pk_bf16_f32 v67, v68, v69
	v_sub_f32_e32 v68, v70, v144
	v_sub_f32_e32 v70, v71, v144
	v_exp_f32_e32 v68, v68
	v_sub_f32_e32 v71, v72, v144
	v_exp_f32_e32 v70, v70
	v_sub_f32_e32 v72, v73, v144
	v_exp_f32_e32 v71, v71
	v_exp_f32_e32 v72, v72
	v_add_f32_e32 v69, v68, v82
	v_add_f32_e32 v69, v70, v69
	v_add_f32_e32 v69, v71, v69
	v_add_f32_e32 v73, v72, v69
	v_cvt_pk_bf16_f32 v68, v68, v70
	v_cvt_pk_bf16_f32 v69, v71, v72
	v_sub_f32_e32 v70, v74, v144
	v_exp_f32_e32 v70, v70
	v_sub_f32_e32 v72, v75, v144
	v_add_f32_e32 v71, v70, v73
	v_sub_f32_e32 v73, v76, v144
	v_exp_f32_e32 v72, v72
	v_sub_f32_e32 v74, v77, v144
	v_exp_f32_e32 v73, v73
	v_exp_f32_e32 v74, v74
	v_add_f32_e32 v71, v72, v71
	v_add_f32_e32 v71, v73, v71
	v_cvt_pk_bf16_f32 v70, v70, v72
	v_add_f32_e32 v75, v74, v71
	v_cvt_pk_bf16_f32 v71, v73, v74
	v_sub_f32_e32 v72, v78, v144
	v_exp_f32_e32 v72, v72
	v_sub_f32_e32 v74, v79, v144
	v_add_f32_e32 v73, v72, v75
	v_sub_f32_e32 v75, v80, v144
	v_exp_f32_e32 v74, v74
	v_sub_f32_e32 v76, v81, v144
	v_exp_f32_e32 v75, v75
	v_exp_f32_e32 v76, v76
	v_add_f32_e32 v73, v74, v73
	v_add_f32_e32 v73, v75, v73
	v_cvt_pk_bf16_f32 v72, v72, v74
	v_add_f32_e32 v77, v76, v73
	v_cvt_pk_bf16_f32 v73, v75, v76
	v_sub_f32_e32 v74, v98, v142
	v_add_f32_e32 v140, v140, v77
	v_sub_f32_e32 v76, v99, v142
	v_exp_f32_e32 v74, v74
	v_sub_f32_e32 v77, v100, v142
	v_exp_f32_e32 v76, v76
	v_sub_f32_e32 v78, v101, v142
	v_exp_f32_e32 v77, v77
	v_exp_f32_e32 v78, v78
	v_add_f32_e32 v75, 0, v74
	v_add_f32_e32 v75, v76, v75
	v_add_f32_e32 v75, v77, v75
	v_add_f32_e32 v79, v78, v75
	v_cvt_pk_bf16_f32 v74, v74, v76
	v_cvt_pk_bf16_f32 v75, v77, v78
	v_sub_f32_e32 v76, v102, v142
	v_exp_f32_e32 v76, v76
	v_sub_f32_e32 v78, v103, v142
	v_add_f32_e32 v77, v76, v79
	v_sub_f32_e32 v79, v104, v142
	v_exp_f32_e32 v78, v78
	v_sub_f32_e32 v80, v105, v142
	v_exp_f32_e32 v79, v79
	v_exp_f32_e32 v80, v80
	v_add_f32_e32 v77, v78, v77
	v_add_f32_e32 v77, v79, v77
	v_cvt_pk_bf16_f32 v76, v76, v78
	v_add_f32_e32 v81, v80, v77
	v_cvt_pk_bf16_f32 v77, v79, v80
	v_sub_f32_e32 v78, v106, v142
	v_exp_f32_e32 v78, v78
	v_sub_f32_e32 v80, v107, v142
	v_add_f32_e32 v79, v78, v81
	v_sub_f32_e32 v81, v108, v142
	v_exp_f32_e32 v80, v80
	v_sub_f32_e32 v83, v109, v142
	v_exp_f32_e32 v81, v81
	v_exp_f32_e32 v83, v83
	v_add_f32_e32 v79, v80, v79
	v_add_f32_e32 v79, v81, v79
	v_cvt_pk_bf16_f32 v78, v78, v80
	v_add_f32_e32 v84, v83, v79
	v_cvt_pk_bf16_f32 v79, v81, v83
	v_sub_f32_e32 v80, v110, v142
	v_exp_f32_e32 v80, v80
	v_sub_f32_e32 v83, v111, v142
	v_or_b32_e32 v82, s15, v135
	v_add_f32_e32 v81, v80, v84
	v_sub_f32_e32 v84, v112, v142
	v_exp_f32_e32 v83, v83
	v_sub_f32_e32 v85, v113, v142
	v_exp_f32_e32 v84, v84
	v_exp_f32_e32 v85, v85
	v_add_f32_e32 v81, v83, v81
	v_add_f32_e32 v81, v84, v81
	v_mul_u32_u24_e32 v82, 0x48, v82
	v_add_f32_e32 v86, v85, v81
	v_lshl_add_u32 v98, v82, 1, v136
	v_cvt_pk_bf16_f32 v80, v80, v83
	v_cvt_pk_bf16_f32 v81, v84, v85
	v_add_f32_e32 v137, v137, v86
	ds_read_b64_tr_b16 v[84:85], v98 offset:20736
	ds_read_b64_tr_b16 v[82:83], v98 offset:18432
	ds_read_b64_tr_b16 v[86:87], v98 offset:18464
	ds_read_b64_tr_b16 v[90:91], v98 offset:23040
	ds_read_b64_tr_b16 v[92:93], v98 offset:25344
	ds_read_b64_tr_b16 v[88:89], v98 offset:20768
	ds_read_b64_tr_b16 v[94:95], v98 offset:23072
	ds_read_b64_tr_b16 v[96:97], v98 offset:25376
	s_waitcnt lgkmcnt(6)
	v_mfma_f32_16x16x32_bf16 v[18:21], v[82:85], v[66:69], v[18:21]
	v_mfma_f32_16x16x32_bf16 v[30:33], v[82:85], v[74:77], v[30:33]
	s_waitcnt lgkmcnt(2)
	v_mfma_f32_16x16x32_bf16 v[22:25], v[86:89], v[66:69], v[22:25]
	v_mfma_f32_16x16x32_bf16 v[26:29], v[86:89], v[74:77], v[26:29]
	v_mfma_f32_16x16x32_bf16 v[18:21], v[90:93], v[70:73], v[18:21]
	v_mfma_f32_16x16x32_bf16 v[30:33], v[90:93], v[78:81], v[30:33]
	s_waitcnt lgkmcnt(0)
	v_mfma_f32_16x16x32_bf16 v[22:25], v[94:97], v[70:73], v[22:25]
	v_mfma_f32_16x16x32_bf16 v[26:29], v[94:97], v[78:81], v[26:29]
	ds_read_b64_tr_b16 v[84:85], v98 offset:20800
	ds_read_b64_tr_b16 v[82:83], v98 offset:18496
	ds_read_b64_tr_b16 v[88:89], v98 offset:20832
	ds_read_b64_tr_b16 v[86:87], v98 offset:18528
	ds_read_b64_tr_b16 v[90:91], v98 offset:23104
	ds_read_b64_tr_b16 v[92:93], v98 offset:25408
	ds_read_b64_tr_b16 v[96:97], v98 offset:25440
	ds_read_b64_tr_b16 v[94:95], v98 offset:23136
	s_waitcnt lgkmcnt(6)
	v_mfma_f32_16x16x32_bf16 v[10:13], v[82:85], v[66:69], v[10:13]
	v_mfma_f32_16x16x32_bf16 v[14:17], v[82:85], v[74:77], v[14:17]
	s_waitcnt lgkmcnt(4)
	v_mfma_f32_16x16x32_bf16 v[2:5], v[86:89], v[66:69], v[2:5]
	v_mfma_f32_16x16x32_bf16 v[6:9], v[86:89], v[74:77], v[6:9]
	s_waitcnt lgkmcnt(2)
	v_mfma_f32_16x16x32_bf16 v[10:13], v[90:93], v[70:73], v[10:13]
	v_mfma_f32_16x16x32_bf16 v[14:17], v[90:93], v[78:81], v[14:17]
	s_waitcnt lgkmcnt(0)
	v_mfma_f32_16x16x32_bf16 v[2:5], v[94:97], v[70:73], v[2:5]
	v_mfma_f32_16x16x32_bf16 v[6:9], v[94:97], v[78:81], v[6:9]
